# SwiGLU output stores: sc1 nt instead of nt
# baseline (speedup 1.0000x reference)
; __device__ __forceinline__ unsigned cvt_pk_bf16(float lo, float hi) { unsigned r; asm volatile("v_cvt_pk_bf16_f32 %0, %1, %2" : "=v"(r) : "v"(lo), "v"(hi)); return r; }
;     __device__ __forceinline__ void operator()(Acc& acc, const Unit& u, int wr, int wc, int fr, int fq) const { scale(acc, u, wr, wc, fr, fq, PC_GA, true); }
;     __device__ __forceinline__ void operator()(Acc& acc, const Unit& u, int wr, int wc, int fr, int fq) const {
;         const int row0 = u.pm * BM + wr * 64 + fr, col0 = u.pn * 128 + wc * 32 + 8 * fq;
; #pragma unroll
;         for (int ai = 0; ai < 2; ++ai)
; #pragma unroll
;             for (int m = 0; m < 4; ++m) {
;                 const int row = row0 + ai * HALF + m * 16;
;                 const float r = rs[u.idx * BM + wr * 64 + fr + ai * HALF + m * 16];
;                 const float c1 = -r * 1.4426950408889634f, r2 = r * r;
;                 f32x4 o[2];
; #pragma unroll
;                 for (int n = 0; n < 2; ++n) {
;                     const f32x4 g = acc[ai][0][m][n], up = acc[ai][1][m][n];
;                     const f32x4 t = g * c1; f32x4 e;
; #pragma unroll
;                     for (int i = 0; i < 4; ++i) e[i] = __builtin_amdgcn_exp2f(t[i]);
;                     const f32x4 d = e + 1.0f; f32x4 q;
; #pragma unroll
;                     for (int i = 0; i < 4; ++i) q[i] = __builtin_amdgcn_rcpf(d[i]);
;                     o[n] = (g * up) * (q * r2);
;                 }
;                 u32x4 w; w.x = cvt_pk_bf16(o[0][0], o[0][1]); w.y = cvt_pk_bf16(o[0][2], o[0][3]); w.z = cvt_pk_bf16(o[1][0], o[1][1]); w.w = cvt_pk_bf16(o[1][2], o[1][3]);
;                 *(u32x4*)(O + (size_t)row * DFF + col0) = w;
.LBB0_610:
	v_lshl_add_u32 v154, s45, 10, v146
	ds_read_b32 v200, v154
	ds_read_b32 v201, v154 offset:64
	ds_read_b32 v202, v154 offset:128
	ds_read_b32 v203, v154 offset:192
	ds_read_b32 v204, v154 offset:512
	ds_read_b32 v205, v154 offset:576
	ds_read_b32 v206, v154 offset:640
	ds_read_b32 v207, v154 offset:704
	v_lshl_or_b32 v156, s47, 7, v147
	v_lshl_add_u32 v151, s20, 8, v144
	v_lshlrev_b32_e32 v156, 1, v156
	v_mov_b32_e32 v198, 1.0
	v_mad_u32_u24 v155, v151, s42, v156
	s_waitcnt lgkmcnt(0)
	v_mul_f32_e32 v158, 0xbfb8aa3b, v200
	v_mul_f32_e32 v160, v200, v200
	v_pk_mul_f32 v[162:163], v[124:125], v[158:159] op_sel_hi:[1,0]
	v_pk_mul_f32 v[164:165], v[126:127], v[158:159] op_sel_hi:[1,0]
	v_pk_mul_f32 v[166:167], v[116:117], v[158:159] op_sel_hi:[1,0]
	v_pk_mul_f32 v[168:169], v[118:119], v[158:159] op_sel_hi:[1,0]
	v_exp_f32_e32 v162, v162
	v_exp_f32_e32 v163, v163
	v_pk_mul_f32 v[120:121], v[124:125], v[120:121]
	v_exp_f32_e32 v164, v164
	v_exp_f32_e32 v165, v165
	v_pk_mul_f32 v[122:123], v[126:127], v[122:123]
	v_exp_f32_e32 v166, v166
	v_exp_f32_e32 v167, v167
	v_pk_mul_f32 v[112:113], v[116:117], v[112:113]
	v_exp_f32_e32 v168, v168
	v_exp_f32_e32 v169, v169
	v_pk_mul_f32 v[114:115], v[118:119], v[114:115]
	v_pk_add_f32 v[162:163], v[162:163], v[198:199] op_sel_hi:[1,0]
	v_pk_add_f32 v[164:165], v[164:165], v[198:199] op_sel_hi:[1,0]
	v_pk_add_f32 v[166:167], v[166:167], v[198:199] op_sel_hi:[1,0]
	v_pk_add_f32 v[168:169], v[168:169], v[198:199] op_sel_hi:[1,0]
	v_rcp_f32_e32 v162, v162
	v_rcp_f32_e32 v163, v163
	v_rcp_f32_e32 v164, v164
	v_rcp_f32_e32 v165, v165
	v_rcp_f32_e32 v166, v166
	v_rcp_f32_e32 v167, v167
	v_rcp_f32_e32 v168, v168
	v_rcp_f32_e32 v169, v169
	v_pk_mul_f32 v[162:163], v[160:161], v[162:163] op_sel_hi:[0,1]
	v_pk_mul_f32 v[164:165], v[160:161], v[164:165] op_sel_hi:[0,1]
	v_pk_mul_f32 v[166:167], v[160:161], v[166:167] op_sel_hi:[0,1]
	v_pk_mul_f32 v[168:169], v[160:161], v[168:169] op_sel_hi:[0,1]
	v_pk_mul_f32 v[120:121], v[120:121], v[162:163]
	v_pk_mul_f32 v[122:123], v[122:123], v[164:165]
	v_pk_mul_f32 v[112:113], v[112:113], v[166:167]
	v_pk_mul_f32 v[114:115], v[114:115], v[168:169]
	v_cvt_pk_bf16_f32 v170, v120, v121
	v_cvt_pk_bf16_f32 v171, v122, v123
	v_cvt_pk_bf16_f32 v172, v112, v113
	v_cvt_pk_bf16_f32 v173, v114, v115
	global_store_dwordx4 v155, v[170:173], s[64:65] sc1 nt
	v_mul_f32_e32 v158, 0xbfb8aa3b, v201
	v_mul_f32_e32 v160, v201, v201
	v_pk_mul_f32 v[162:163], v[108:109], v[158:159] op_sel_hi:[1,0]
	v_pk_mul_f32 v[164:165], v[110:111], v[158:159] op_sel_hi:[1,0]
	v_pk_mul_f32 v[166:167], v[100:101], v[158:159] op_sel_hi:[1,0]
	v_pk_mul_f32 v[168:169], v[102:103], v[158:159] op_sel_hi:[1,0]
	v_exp_f32_e32 v162, v162
	v_exp_f32_e32 v163, v163
	v_pk_mul_f32 v[104:105], v[108:109], v[104:105]
	v_exp_f32_e32 v164, v164
	v_exp_f32_e32 v165, v165
	v_pk_mul_f32 v[106:107], v[110:111], v[106:107]
	v_exp_f32_e32 v166, v166
	v_exp_f32_e32 v167, v167
	v_pk_mul_f32 v[96:97], v[100:101], v[96:97]
	v_exp_f32_e32 v168, v168
	v_exp_f32_e32 v169, v169
	v_pk_mul_f32 v[98:99], v[102:103], v[98:99]
	v_pk_add_f32 v[162:163], v[162:163], v[198:199] op_sel_hi:[1,0]
	v_pk_add_f32 v[164:165], v[164:165], v[198:199] op_sel_hi:[1,0]
	v_pk_add_f32 v[166:167], v[166:167], v[198:199] op_sel_hi:[1,0]
	v_pk_add_f32 v[168:169], v[168:169], v[198:199] op_sel_hi:[1,0]
	v_rcp_f32_e32 v162, v162
	v_rcp_f32_e32 v163, v163
	v_rcp_f32_e32 v164, v164
	v_rcp_f32_e32 v165, v165
	v_rcp_f32_e32 v166, v166
	v_rcp_f32_e32 v167, v167
	v_rcp_f32_e32 v168, v168
	v_rcp_f32_e32 v169, v169
	v_pk_mul_f32 v[162:163], v[160:161], v[162:163] op_sel_hi:[0,1]
	v_pk_mul_f32 v[164:165], v[160:161], v[164:165] op_sel_hi:[0,1]
	v_pk_mul_f32 v[166:167], v[160:161], v[166:167] op_sel_hi:[0,1]
	v_pk_mul_f32 v[168:169], v[160:161], v[168:169] op_sel_hi:[0,1]
	v_pk_mul_f32 v[104:105], v[104:105], v[162:163]
	v_pk_mul_f32 v[106:107], v[106:107], v[164:165]
	v_pk_mul_f32 v[96:97], v[96:97], v[166:167]
	v_pk_mul_f32 v[98:99], v[98:99], v[168:169]
	v_cvt_pk_bf16_f32 v176, v104, v105
	v_cvt_pk_bf16_f32 v177, v106, v107
	v_cvt_pk_bf16_f32 v178, v96, v97
	v_cvt_pk_bf16_f32 v179, v98, v99
	v_add_u32_e32 v175, 0x16000, v155
	global_store_dwordx4 v175, v[176:179], s[64:65] sc1 nt
	v_mul_f32_e32 v158, 0xbfb8aa3b, v202
	v_mul_f32_e32 v160, v202, v202
	v_pk_mul_f32 v[162:163], v[92:93], v[158:159] op_sel_hi:[1,0]
	v_pk_mul_f32 v[164:165], v[94:95], v[158:159] op_sel_hi:[1,0]
	v_pk_mul_f32 v[166:167], v[84:85], v[158:159] op_sel_hi:[1,0]
	v_pk_mul_f32 v[168:169], v[86:87], v[158:159] op_sel_hi:[1,0]
	v_exp_f32_e32 v162, v162
	v_exp_f32_e32 v163, v163
	v_pk_mul_f32 v[88:89], v[92:93], v[88:89]
	v_exp_f32_e32 v164, v164
	v_exp_f32_e32 v165, v165
	v_pk_mul_f32 v[90:91], v[94:95], v[90:91]
	v_exp_f32_e32 v166, v166
	v_exp_f32_e32 v167, v167
	v_pk_mul_f32 v[80:81], v[84:85], v[80:81]
	v_exp_f32_e32 v168, v168
	v_exp_f32_e32 v169, v169
	v_pk_mul_f32 v[82:83], v[86:87], v[82:83]
	v_pk_add_f32 v[162:163], v[162:163], v[198:199] op_sel_hi:[1,0]
	v_pk_add_f32 v[164:165], v[164:165], v[198:199] op_sel_hi:[1,0]
	v_pk_add_f32 v[166:167], v[166:167], v[198:199] op_sel_hi:[1,0]
	v_pk_add_f32 v[168:169], v[168:169], v[198:199] op_sel_hi:[1,0]
	v_rcp_f32_e32 v162, v162
	v_rcp_f32_e32 v163, v163
	v_rcp_f32_e32 v164, v164
	v_rcp_f32_e32 v165, v165
	v_rcp_f32_e32 v166, v166
	v_rcp_f32_e32 v167, v167
	v_rcp_f32_e32 v168, v168
	v_rcp_f32_e32 v169, v169
	v_pk_mul_f32 v[162:163], v[160:161], v[162:163] op_sel_hi:[0,1]
	v_pk_mul_f32 v[164:165], v[160:161], v[164:165] op_sel_hi:[0,1]
	v_pk_mul_f32 v[166:167], v[160:161], v[166:167] op_sel_hi:[0,1]
	v_pk_mul_f32 v[168:169], v[160:161], v[168:169] op_sel_hi:[0,1]
; __device__ __forceinline__ unsigned cvt_pk_bf16(float lo, float hi) { unsigned r; asm volatile("v_cvt_pk_bf16_f32 %0, %1, %2" : "=v"(r) : "v"(lo), "v"(hi)); return r; }
;     __device__ __forceinline__ void operator()(Acc& acc, const Unit& u, int wr, int wc, int fr, int fq) const {
;     ...
;             for (int m = 0; m < 4; ++m) {
;                 const int row = row0 + ai * HALF + m * 16;
;                 const float r = rs[u.idx * BM + wr * 64 + fr + ai * HALF + m * 16];
;                 const float c1 = -r * 1.4426950408889634f, r2 = r * r;
;                 f32x4 o[2];
; #pragma unroll
;                 for (int n = 0; n < 2; ++n) {
;                     const f32x4 g = acc[ai][0][m][n], up = acc[ai][1][m][n];
;                     const f32x4 t = g * c1; f32x4 e;
; #pragma unroll
;                     for (int i = 0; i < 4; ++i) e[i] = __builtin_amdgcn_exp2f(t[i]);
;                     const f32x4 d = e + 1.0f; f32x4 q;
; #pragma unroll
;                     for (int i = 0; i < 4; ++i) q[i] = __builtin_amdgcn_rcpf(d[i]);
;                     o[n] = (g * up) * (q * r2);
;                 }
;                 u32x4 w; w.x = cvt_pk_bf16(o[0][0], o[0][1]); w.y = cvt_pk_bf16(o[0][2], o[0][3]); w.z = cvt_pk_bf16(o[1][0], o[1][1]); w.w = cvt_pk_bf16(o[1][2], o[1][3]);
;                 *(u32x4*)(O + (size_t)row * DFF + col0) = w;
	v_pk_mul_f32 v[88:89], v[88:89], v[162:163]
	v_pk_mul_f32 v[90:91], v[90:91], v[164:165]
	v_pk_mul_f32 v[80:81], v[80:81], v[166:167]
	v_pk_mul_f32 v[82:83], v[82:83], v[168:169]
	v_cvt_pk_bf16_f32 v170, v88, v89
	v_cvt_pk_bf16_f32 v171, v90, v91
	v_cvt_pk_bf16_f32 v172, v80, v81
	v_cvt_pk_bf16_f32 v173, v82, v83
	v_add_u32_e32 v174, 0x2c000, v155
	global_store_dwordx4 v174, v[170:173], s[64:65] sc1 nt
	v_mul_f32_e32 v158, 0xbfb8aa3b, v203
	v_mul_f32_e32 v160, v203, v203
	v_pk_mul_f32 v[162:163], v[76:77], v[158:159] op_sel_hi:[1,0]
	v_pk_mul_f32 v[164:165], v[78:79], v[158:159] op_sel_hi:[1,0]
	v_pk_mul_f32 v[166:167], v[68:69], v[158:159] op_sel_hi:[1,0]
	v_pk_mul_f32 v[168:169], v[70:71], v[158:159] op_sel_hi:[1,0]
	v_exp_f32_e32 v162, v162
	v_exp_f32_e32 v163, v163
	v_pk_mul_f32 v[72:73], v[76:77], v[72:73]
	v_exp_f32_e32 v164, v164
	v_exp_f32_e32 v165, v165
	v_pk_mul_f32 v[74:75], v[78:79], v[74:75]
	v_exp_f32_e32 v166, v166
	v_exp_f32_e32 v167, v167
	v_pk_mul_f32 v[64:65], v[68:69], v[64:65]
	v_exp_f32_e32 v168, v168
	v_exp_f32_e32 v169, v169
	v_pk_mul_f32 v[66:67], v[70:71], v[66:67]
	v_pk_add_f32 v[162:163], v[162:163], v[198:199] op_sel_hi:[1,0]
	v_pk_add_f32 v[164:165], v[164:165], v[198:199] op_sel_hi:[1,0]
	v_pk_add_f32 v[166:167], v[166:167], v[198:199] op_sel_hi:[1,0]
	v_pk_add_f32 v[168:169], v[168:169], v[198:199] op_sel_hi:[1,0]
	v_rcp_f32_e32 v162, v162
	v_rcp_f32_e32 v163, v163
	v_rcp_f32_e32 v164, v164
	v_rcp_f32_e32 v165, v165
	v_rcp_f32_e32 v166, v166
	v_rcp_f32_e32 v167, v167
	v_rcp_f32_e32 v168, v168
	v_rcp_f32_e32 v169, v169
	v_pk_mul_f32 v[162:163], v[160:161], v[162:163] op_sel_hi:[0,1]
	v_pk_mul_f32 v[164:165], v[160:161], v[164:165] op_sel_hi:[0,1]
	v_pk_mul_f32 v[166:167], v[160:161], v[166:167] op_sel_hi:[0,1]
	v_pk_mul_f32 v[168:169], v[160:161], v[168:169] op_sel_hi:[0,1]
	v_pk_mul_f32 v[72:73], v[72:73], v[162:163]
	v_pk_mul_f32 v[74:75], v[74:75], v[164:165]
	v_pk_mul_f32 v[64:65], v[64:65], v[166:167]
	v_pk_mul_f32 v[66:67], v[66:67], v[168:169]
	v_cvt_pk_bf16_f32 v176, v72, v73
	v_cvt_pk_bf16_f32 v177, v74, v75
	v_cvt_pk_bf16_f32 v178, v64, v65
	v_cvt_pk_bf16_f32 v179, v66, v67
	v_add_u32_e32 v175, 0x42000, v155
	global_store_dwordx4 v175, v[176:179], s[64:65] sc1 nt
	v_mul_f32_e32 v158, 0xbfb8aa3b, v204
	v_mul_f32_e32 v160, v204, v204
	v_pk_mul_f32 v[162:163], v[60:61], v[158:159] op_sel_hi:[1,0]
	v_pk_mul_f32 v[164:165], v[62:63], v[158:159] op_sel_hi:[1,0]
	v_pk_mul_f32 v[166:167], v[52:53], v[158:159] op_sel_hi:[1,0]
	v_pk_mul_f32 v[168:169], v[54:55], v[158:159] op_sel_hi:[1,0]
	v_exp_f32_e32 v162, v162
	v_exp_f32_e32 v163, v163
	v_pk_mul_f32 v[56:57], v[60:61], v[56:57]
	v_exp_f32_e32 v164, v164
	v_exp_f32_e32 v165, v165
	v_pk_mul_f32 v[58:59], v[62:63], v[58:59]
	v_exp_f32_e32 v166, v166
	v_exp_f32_e32 v167, v167
	v_pk_mul_f32 v[48:49], v[52:53], v[48:49]
	v_exp_f32_e32 v168, v168
	v_exp_f32_e32 v169, v169
	v_pk_mul_f32 v[50:51], v[54:55], v[50:51]
	v_pk_add_f32 v[162:163], v[162:163], v[198:199] op_sel_hi:[1,0]
	v_pk_add_f32 v[164:165], v[164:165], v[198:199] op_sel_hi:[1,0]
	v_pk_add_f32 v[166:167], v[166:167], v[198:199] op_sel_hi:[1,0]
	v_pk_add_f32 v[168:169], v[168:169], v[198:199] op_sel_hi:[1,0]
	v_rcp_f32_e32 v162, v162
	v_rcp_f32_e32 v163, v163
	v_rcp_f32_e32 v164, v164
	v_rcp_f32_e32 v165, v165
	v_rcp_f32_e32 v166, v166
	v_rcp_f32_e32 v167, v167
	v_rcp_f32_e32 v168, v168
	v_rcp_f32_e32 v169, v169
	v_pk_mul_f32 v[162:163], v[160:161], v[162:163] op_sel_hi:[0,1]
	v_pk_mul_f32 v[164:165], v[160:161], v[164:165] op_sel_hi:[0,1]
	v_pk_mul_f32 v[166:167], v[160:161], v[166:167] op_sel_hi:[0,1]
	v_pk_mul_f32 v[168:169], v[160:161], v[168:169] op_sel_hi:[0,1]
	v_pk_mul_f32 v[56:57], v[56:57], v[162:163]
	v_pk_mul_f32 v[58:59], v[58:59], v[164:165]
	v_pk_mul_f32 v[48:49], v[48:49], v[166:167]
	v_pk_mul_f32 v[50:51], v[50:51], v[168:169]
	v_cvt_pk_bf16_f32 v170, v56, v57
	v_cvt_pk_bf16_f32 v171, v58, v59
	v_cvt_pk_bf16_f32 v172, v48, v49
	v_cvt_pk_bf16_f32 v173, v50, v51
	v_add_u32_e32 v174, 0xb0000, v155
	global_store_dwordx4 v174, v[170:173], s[64:65] sc1 nt
	v_mul_f32_e32 v158, 0xbfb8aa3b, v205
	v_mul_f32_e32 v160, v205, v205
	v_pk_mul_f32 v[162:163], v[44:45], v[158:159] op_sel_hi:[1,0]
	v_pk_mul_f32 v[164:165], v[46:47], v[158:159] op_sel_hi:[1,0]
	v_pk_mul_f32 v[166:167], v[36:37], v[158:159] op_sel_hi:[1,0]
	v_pk_mul_f32 v[168:169], v[38:39], v[158:159] op_sel_hi:[1,0]
	v_exp_f32_e32 v162, v162
	v_exp_f32_e32 v163, v163
	v_pk_mul_f32 v[40:41], v[44:45], v[40:41]
	v_exp_f32_e32 v164, v164
	v_exp_f32_e32 v165, v165
	v_pk_mul_f32 v[42:43], v[46:47], v[42:43]
	v_exp_f32_e32 v166, v166
	v_exp_f32_e32 v167, v167
	v_pk_mul_f32 v[32:33], v[36:37], v[32:33]
	v_exp_f32_e32 v168, v168
	v_exp_f32_e32 v169, v169
	v_pk_mul_f32 v[34:35], v[38:39], v[34:35]
	v_pk_add_f32 v[162:163], v[162:163], v[198:199] op_sel_hi:[1,0]
; __device__ __forceinline__ unsigned cvt_pk_bf16(float lo, float hi) { unsigned r; asm volatile("v_cvt_pk_bf16_f32 %0, %1, %2" : "=v"(r) : "v"(lo), "v"(hi)); return r; }
; #define PG8_BAR __builtin_amdgcn_s_barrier()
;     __device__ __forceinline__ void operator()(Acc& acc, const Unit& u, int wr, int wc, int fr, int fq) const {
;     ...
;             for (int m = 0; m < 4; ++m) {
;                 const int row = row0 + ai * HALF + m * 16;
;                 const float r = rs[u.idx * BM + wr * 64 + fr + ai * HALF + m * 16];
;                 const float c1 = -r * 1.4426950408889634f, r2 = r * r;
;                 f32x4 o[2];
; #pragma unroll
;                 for (int n = 0; n < 2; ++n) {
;                     const f32x4 g = acc[ai][0][m][n], up = acc[ai][1][m][n];
;                     const f32x4 t = g * c1; f32x4 e;
; #pragma unroll
;                     for (int i = 0; i < 4; ++i) e[i] = __builtin_amdgcn_exp2f(t[i]);
;                     const f32x4 d = e + 1.0f; f32x4 q;
; #pragma unroll
;                     for (int i = 0; i < 4; ++i) q[i] = __builtin_amdgcn_rcpf(d[i]);
;                     o[n] = (g * up) * (q * r2);
;                 }
;                 u32x4 w; w.x = cvt_pk_bf16(o[0][0], o[0][1]); w.y = cvt_pk_bf16(o[0][2], o[0][3]); w.z = cvt_pk_bf16(o[1][0], o[1][1]); w.w = cvt_pk_bf16(o[1][2], o[1][3]);
;                 *(u32x4*)(O + (size_t)row * DFF + col0) = w;
; template <class Epi, class Sched, bool ALIGN_EPI>
; __device__ __forceinline__ void gemm_phase(LAS unsigned char* lds, const Gemm g, const Sched& S, const Epi& E) {
;     ...
;         if constexpr (ALIGN_EPI) { if (wr == 0) PG8_BAR; }
;         E(acc, cur, wr, wc, fr, fq);
;         if (!has_next) break;
; #pragma unroll
;         for (int a = 0; a < 2; ++a)
; #pragma unroll
;             for (int b = 0; b < 2; ++b)
; #pragma unroll
;                 for (int m = 0; m < 4; ++m)
; #pragma unroll
;                     for (int n = 0; n < 2; ++n) acc[a][b][m][n] = (f32x4){0.f, 0.f, 0.f, 0.f};
;         cur = nxt; cA = nA; cB = nB; ++ui;
;         if constexpr (ALIGN_EPI) { if (wr == 1) PG8_BAR; }
	v_pk_add_f32 v[164:165], v[164:165], v[198:199] op_sel_hi:[1,0]
	v_pk_add_f32 v[166:167], v[166:167], v[198:199] op_sel_hi:[1,0]
	v_pk_add_f32 v[168:169], v[168:169], v[198:199] op_sel_hi:[1,0]
	v_rcp_f32_e32 v162, v162
	v_rcp_f32_e32 v163, v163
	v_rcp_f32_e32 v164, v164
	v_rcp_f32_e32 v165, v165
	v_rcp_f32_e32 v166, v166
	v_rcp_f32_e32 v167, v167
	v_rcp_f32_e32 v168, v168
	v_rcp_f32_e32 v169, v169
	v_pk_mul_f32 v[162:163], v[160:161], v[162:163] op_sel_hi:[0,1]
	v_pk_mul_f32 v[164:165], v[160:161], v[164:165] op_sel_hi:[0,1]
	v_pk_mul_f32 v[166:167], v[160:161], v[166:167] op_sel_hi:[0,1]
	v_pk_mul_f32 v[168:169], v[160:161], v[168:169] op_sel_hi:[0,1]
	v_pk_mul_f32 v[40:41], v[40:41], v[162:163]
	v_pk_mul_f32 v[42:43], v[42:43], v[164:165]
	v_pk_mul_f32 v[32:33], v[32:33], v[166:167]
	v_pk_mul_f32 v[34:35], v[34:35], v[168:169]
	v_cvt_pk_bf16_f32 v176, v40, v41
	v_cvt_pk_bf16_f32 v177, v42, v43
	v_cvt_pk_bf16_f32 v178, v32, v33
	v_cvt_pk_bf16_f32 v179, v34, v35
	v_add_u32_e32 v175, 0xc6000, v155
	global_store_dwordx4 v175, v[176:179], s[64:65] sc1 nt
	v_mul_f32_e32 v158, 0xbfb8aa3b, v206
	v_mul_f32_e32 v160, v206, v206
	v_pk_mul_f32 v[162:163], v[28:29], v[158:159] op_sel_hi:[1,0]
	v_pk_mul_f32 v[164:165], v[30:31], v[158:159] op_sel_hi:[1,0]
	v_pk_mul_f32 v[166:167], v[20:21], v[158:159] op_sel_hi:[1,0]
	v_pk_mul_f32 v[168:169], v[22:23], v[158:159] op_sel_hi:[1,0]
	v_exp_f32_e32 v162, v162
	v_exp_f32_e32 v163, v163
	v_pk_mul_f32 v[24:25], v[28:29], v[24:25]
	v_exp_f32_e32 v164, v164
	v_exp_f32_e32 v165, v165
	v_pk_mul_f32 v[26:27], v[30:31], v[26:27]
	v_exp_f32_e32 v166, v166
	v_exp_f32_e32 v167, v167
	v_pk_mul_f32 v[16:17], v[20:21], v[16:17]
	v_exp_f32_e32 v168, v168
	v_exp_f32_e32 v169, v169
	v_pk_mul_f32 v[18:19], v[22:23], v[18:19]
	v_pk_add_f32 v[162:163], v[162:163], v[198:199] op_sel_hi:[1,0]
	v_pk_add_f32 v[164:165], v[164:165], v[198:199] op_sel_hi:[1,0]
	v_pk_add_f32 v[166:167], v[166:167], v[198:199] op_sel_hi:[1,0]
	v_pk_add_f32 v[168:169], v[168:169], v[198:199] op_sel_hi:[1,0]
	v_rcp_f32_e32 v162, v162
	v_rcp_f32_e32 v163, v163
	v_rcp_f32_e32 v164, v164
	v_rcp_f32_e32 v165, v165
	v_rcp_f32_e32 v166, v166
	v_rcp_f32_e32 v167, v167
	v_rcp_f32_e32 v168, v168
	v_rcp_f32_e32 v169, v169
	v_pk_mul_f32 v[162:163], v[160:161], v[162:163] op_sel_hi:[0,1]
	v_pk_mul_f32 v[164:165], v[160:161], v[164:165] op_sel_hi:[0,1]
	v_pk_mul_f32 v[166:167], v[160:161], v[166:167] op_sel_hi:[0,1]
	v_pk_mul_f32 v[168:169], v[160:161], v[168:169] op_sel_hi:[0,1]
	v_pk_mul_f32 v[24:25], v[24:25], v[162:163]
	v_pk_mul_f32 v[26:27], v[26:27], v[164:165]
	v_pk_mul_f32 v[16:17], v[16:17], v[166:167]
	v_pk_mul_f32 v[18:19], v[18:19], v[168:169]
	v_cvt_pk_bf16_f32 v170, v24, v25
	v_cvt_pk_bf16_f32 v171, v26, v27
	v_cvt_pk_bf16_f32 v172, v16, v17
	v_cvt_pk_bf16_f32 v173, v18, v19
	v_add_u32_e32 v174, 0xdc000, v155
	global_store_dwordx4 v174, v[170:173], s[64:65] sc1 nt
	v_mul_f32_e32 v158, 0xbfb8aa3b, v207
	v_mul_f32_e32 v160, v207, v207
	v_pk_mul_f32 v[162:163], v[12:13], v[158:159] op_sel_hi:[1,0]
	v_pk_mul_f32 v[164:165], v[14:15], v[158:159] op_sel_hi:[1,0]
	v_pk_mul_f32 v[166:167], v[4:5], v[158:159] op_sel_hi:[1,0]
	v_pk_mul_f32 v[168:169], v[6:7], v[158:159] op_sel_hi:[1,0]
	v_exp_f32_e32 v162, v162
	v_exp_f32_e32 v163, v163
	v_pk_mul_f32 v[8:9], v[12:13], v[8:9]
	v_exp_f32_e32 v164, v164
	v_exp_f32_e32 v165, v165
	v_pk_mul_f32 v[10:11], v[14:15], v[10:11]
	v_exp_f32_e32 v166, v166
	v_exp_f32_e32 v167, v167
	v_pk_mul_f32 v[0:1], v[4:5], v[0:1]
	v_exp_f32_e32 v168, v168
	v_exp_f32_e32 v169, v169
	v_pk_mul_f32 v[2:3], v[6:7], v[2:3]
	v_pk_add_f32 v[162:163], v[162:163], v[198:199] op_sel_hi:[1,0]
	v_pk_add_f32 v[164:165], v[164:165], v[198:199] op_sel_hi:[1,0]
	v_pk_add_f32 v[166:167], v[166:167], v[198:199] op_sel_hi:[1,0]
	v_pk_add_f32 v[168:169], v[168:169], v[198:199] op_sel_hi:[1,0]
	v_rcp_f32_e32 v162, v162
	v_rcp_f32_e32 v163, v163
	v_rcp_f32_e32 v164, v164
	v_rcp_f32_e32 v165, v165
	v_rcp_f32_e32 v166, v166
	v_rcp_f32_e32 v167, v167
	v_rcp_f32_e32 v168, v168
	v_rcp_f32_e32 v169, v169
	v_pk_mul_f32 v[162:163], v[160:161], v[162:163] op_sel_hi:[0,1]
	v_pk_mul_f32 v[164:165], v[160:161], v[164:165] op_sel_hi:[0,1]
	v_pk_mul_f32 v[166:167], v[160:161], v[166:167] op_sel_hi:[0,1]
	v_pk_mul_f32 v[168:169], v[160:161], v[168:169] op_sel_hi:[0,1]
	v_pk_mul_f32 v[8:9], v[8:9], v[162:163]
	v_pk_mul_f32 v[10:11], v[10:11], v[164:165]
	v_pk_mul_f32 v[0:1], v[0:1], v[166:167]
	v_pk_mul_f32 v[2:3], v[2:3], v[168:169]
	v_cvt_pk_bf16_f32 v176, v8, v9
	v_cvt_pk_bf16_f32 v177, v10, v11
	v_cvt_pk_bf16_f32 v178, v0, v1
	v_cvt_pk_bf16_f32 v179, v2, v3
	v_add_u32_e32 v175, 0xf2000, v155
	global_store_dwordx4 v175, v[176:179], s[64:65] sc1 nt
	s_andn2_b64 vcc, exec, s[2:3]
	s_mov_b64 s[2:3], -1
	s_mov_b32 s101, 1
	s_cbranch_vccnz .LBB0_603
	s_andn2_b64 vcc, exec, s[6:7]
	s_cbranch_vccnz .LBB0_602
	s_barrier
	s_branch .LBB0_602

; __device__ __forceinline__ unsigned cvt_pk_bf16(float lo, float hi) { unsigned r; asm volatile("v_cvt_pk_bf16_f32 %0, %1, %2" : "=v"(r) : "v"(lo), "v"(hi)); return r; }
;     __device__ __forceinline__ void operator()(Acc& acc, const Unit& u, int wr, int wc, int fr, int fq) const { scale(acc, u, wr, wc, fr, fq, PC_GA, true); }
;     __device__ __forceinline__ void operator()(Acc& acc, const Unit& u, int wr, int wc, int fr, int fq) const {
;         const int row0 = u.pm * BM + wr * 64 + fr, col0 = u.pn * 128 + wc * 32 + 8 * fq;
; #pragma unroll
;         for (int ai = 0; ai < 2; ++ai)
; #pragma unroll
;             for (int m = 0; m < 4; ++m) {
;                 const int row = row0 + ai * HALF + m * 16;
;                 const float r = rs[u.idx * BM + wr * 64 + fr + ai * HALF + m * 16];
;                 const float c1 = -r * 1.4426950408889634f, r2 = r * r;
;                 f32x4 o[2];
; #pragma unroll
;                 for (int n = 0; n < 2; ++n) {
;                     const f32x4 g = acc[ai][0][m][n], up = acc[ai][1][m][n];
;                     const f32x4 t = g * c1; f32x4 e;
; #pragma unroll
;                     for (int i = 0; i < 4; ++i) e[i] = __builtin_amdgcn_exp2f(t[i]);
;                     const f32x4 d = e + 1.0f; f32x4 q;
; #pragma unroll
;                     for (int i = 0; i < 4; ++i) q[i] = __builtin_amdgcn_rcpf(d[i]);
;                     o[n] = (g * up) * (q * r2);
;                 }
;                 u32x4 w; w.x = cvt_pk_bf16(o[0][0], o[0][1]); w.y = cvt_pk_bf16(o[0][2], o[0][3]); w.z = cvt_pk_bf16(o[1][0], o[1][1]); w.w = cvt_pk_bf16(o[1][2], o[1][3]);
;                 *(u32x4*)(O + (size_t)row * DFF + col0) = w;
.LBB0_1616:
	v_lshl_add_u32 v154, s43, 10, v146
	ds_read_b32 v200, v154
	ds_read_b32 v201, v154 offset:64
	ds_read_b32 v202, v154 offset:128
	ds_read_b32 v203, v154 offset:192
	ds_read_b32 v204, v154 offset:512
	ds_read_b32 v205, v154 offset:576
	ds_read_b32 v206, v154 offset:640
	ds_read_b32 v207, v154 offset:704
	v_lshl_or_b32 v156, s44, 7, v147
	v_lshl_add_u32 v151, s18, 8, v144
	v_lshlrev_b32_e32 v156, 1, v156
	v_mov_b32_e32 v198, 1.0
	v_mad_u32_u24 v155, v151, s40, v156
	s_waitcnt lgkmcnt(0)
	v_mul_f32_e32 v158, 0xbfb8aa3b, v200
	v_mul_f32_e32 v160, v200, v200
	v_pk_mul_f32 v[162:163], v[124:125], v[158:159] op_sel_hi:[1,0]
	v_pk_mul_f32 v[164:165], v[126:127], v[158:159] op_sel_hi:[1,0]
	v_pk_mul_f32 v[166:167], v[116:117], v[158:159] op_sel_hi:[1,0]
	v_pk_mul_f32 v[168:169], v[118:119], v[158:159] op_sel_hi:[1,0]
	v_exp_f32_e32 v162, v162
	v_exp_f32_e32 v163, v163
	v_pk_mul_f32 v[120:121], v[124:125], v[120:121]
	v_exp_f32_e32 v164, v164
	v_exp_f32_e32 v165, v165
	v_pk_mul_f32 v[122:123], v[126:127], v[122:123]
	v_exp_f32_e32 v166, v166
	v_exp_f32_e32 v167, v167
	v_pk_mul_f32 v[112:113], v[116:117], v[112:113]
	v_exp_f32_e32 v168, v168
	v_exp_f32_e32 v169, v169
	v_pk_mul_f32 v[114:115], v[118:119], v[114:115]
	v_pk_add_f32 v[162:163], v[162:163], v[198:199] op_sel_hi:[1,0]
	v_pk_add_f32 v[164:165], v[164:165], v[198:199] op_sel_hi:[1,0]
	v_pk_add_f32 v[166:167], v[166:167], v[198:199] op_sel_hi:[1,0]
	v_pk_add_f32 v[168:169], v[168:169], v[198:199] op_sel_hi:[1,0]
	v_rcp_f32_e32 v162, v162
	v_rcp_f32_e32 v163, v163
	v_rcp_f32_e32 v164, v164
	v_rcp_f32_e32 v165, v165
	v_rcp_f32_e32 v166, v166
	v_rcp_f32_e32 v167, v167
	v_rcp_f32_e32 v168, v168
	v_rcp_f32_e32 v169, v169
	v_pk_mul_f32 v[162:163], v[160:161], v[162:163] op_sel_hi:[0,1]
	v_pk_mul_f32 v[164:165], v[160:161], v[164:165] op_sel_hi:[0,1]
	v_pk_mul_f32 v[166:167], v[160:161], v[166:167] op_sel_hi:[0,1]
	v_pk_mul_f32 v[168:169], v[160:161], v[168:169] op_sel_hi:[0,1]
	v_pk_mul_f32 v[120:121], v[120:121], v[162:163]
	v_pk_mul_f32 v[122:123], v[122:123], v[164:165]
	v_pk_mul_f32 v[112:113], v[112:113], v[166:167]
	v_pk_mul_f32 v[114:115], v[114:115], v[168:169]
	v_cvt_pk_bf16_f32 v170, v120, v121
	v_cvt_pk_bf16_f32 v171, v122, v123
	v_cvt_pk_bf16_f32 v172, v112, v113
	v_cvt_pk_bf16_f32 v173, v114, v115
	global_store_dwordx4 v155, v[170:173], s[64:65] sc1 nt
	v_mul_f32_e32 v158, 0xbfb8aa3b, v201
	v_mul_f32_e32 v160, v201, v201
	v_pk_mul_f32 v[162:163], v[108:109], v[158:159] op_sel_hi:[1,0]
	v_pk_mul_f32 v[164:165], v[110:111], v[158:159] op_sel_hi:[1,0]
	v_pk_mul_f32 v[166:167], v[100:101], v[158:159] op_sel_hi:[1,0]
	v_pk_mul_f32 v[168:169], v[102:103], v[158:159] op_sel_hi:[1,0]
	v_exp_f32_e32 v162, v162
	v_exp_f32_e32 v163, v163
	v_pk_mul_f32 v[104:105], v[108:109], v[104:105]
	v_exp_f32_e32 v164, v164
	v_exp_f32_e32 v165, v165
	v_pk_mul_f32 v[106:107], v[110:111], v[106:107]
	v_exp_f32_e32 v166, v166
	v_exp_f32_e32 v167, v167
	v_pk_mul_f32 v[96:97], v[100:101], v[96:97]
	v_exp_f32_e32 v168, v168
	v_exp_f32_e32 v169, v169
	v_pk_mul_f32 v[98:99], v[102:103], v[98:99]
	v_pk_add_f32 v[162:163], v[162:163], v[198:199] op_sel_hi:[1,0]
	v_pk_add_f32 v[164:165], v[164:165], v[198:199] op_sel_hi:[1,0]
	v_pk_add_f32 v[166:167], v[166:167], v[198:199] op_sel_hi:[1,0]
	v_pk_add_f32 v[168:169], v[168:169], v[198:199] op_sel_hi:[1,0]
	v_rcp_f32_e32 v162, v162
	v_rcp_f32_e32 v163, v163
	v_rcp_f32_e32 v164, v164
	v_rcp_f32_e32 v165, v165
	v_rcp_f32_e32 v166, v166
	v_rcp_f32_e32 v167, v167
	v_rcp_f32_e32 v168, v168
	v_rcp_f32_e32 v169, v169
	v_pk_mul_f32 v[162:163], v[160:161], v[162:163] op_sel_hi:[0,1]
	v_pk_mul_f32 v[164:165], v[160:161], v[164:165] op_sel_hi:[0,1]
	v_pk_mul_f32 v[166:167], v[160:161], v[166:167] op_sel_hi:[0,1]
	v_pk_mul_f32 v[168:169], v[160:161], v[168:169] op_sel_hi:[0,1]
	v_pk_mul_f32 v[104:105], v[104:105], v[162:163]
	v_pk_mul_f32 v[106:107], v[106:107], v[164:165]
	v_pk_mul_f32 v[96:97], v[96:97], v[166:167]
	v_pk_mul_f32 v[98:99], v[98:99], v[168:169]
	v_cvt_pk_bf16_f32 v176, v104, v105
	v_cvt_pk_bf16_f32 v177, v106, v107
	v_cvt_pk_bf16_f32 v178, v96, v97
	v_cvt_pk_bf16_f32 v179, v98, v99
	v_add_u32_e32 v175, 0x16000, v155
	global_store_dwordx4 v175, v[176:179], s[64:65] sc1 nt
	v_mul_f32_e32 v158, 0xbfb8aa3b, v202
	v_mul_f32_e32 v160, v202, v202
	v_pk_mul_f32 v[162:163], v[92:93], v[158:159] op_sel_hi:[1,0]
	v_pk_mul_f32 v[164:165], v[94:95], v[158:159] op_sel_hi:[1,0]
	v_pk_mul_f32 v[166:167], v[84:85], v[158:159] op_sel_hi:[1,0]
	v_pk_mul_f32 v[168:169], v[86:87], v[158:159] op_sel_hi:[1,0]
	v_exp_f32_e32 v162, v162
	v_exp_f32_e32 v163, v163
	v_pk_mul_f32 v[88:89], v[92:93], v[88:89]
	v_exp_f32_e32 v164, v164
	v_exp_f32_e32 v165, v165
	v_pk_mul_f32 v[90:91], v[94:95], v[90:91]
	v_exp_f32_e32 v166, v166
	v_exp_f32_e32 v167, v167
	v_pk_mul_f32 v[80:81], v[84:85], v[80:81]
	v_exp_f32_e32 v168, v168
	v_exp_f32_e32 v169, v169
	v_pk_mul_f32 v[82:83], v[86:87], v[82:83]
	v_pk_add_f32 v[162:163], v[162:163], v[198:199] op_sel_hi:[1,0]
	v_pk_add_f32 v[164:165], v[164:165], v[198:199] op_sel_hi:[1,0]
	v_pk_add_f32 v[166:167], v[166:167], v[198:199] op_sel_hi:[1,0]
	v_pk_add_f32 v[168:169], v[168:169], v[198:199] op_sel_hi:[1,0]
	v_rcp_f32_e32 v162, v162
	v_rcp_f32_e32 v163, v163
	v_rcp_f32_e32 v164, v164
	v_rcp_f32_e32 v165, v165
	v_rcp_f32_e32 v166, v166
	v_rcp_f32_e32 v167, v167
	v_rcp_f32_e32 v168, v168
	v_rcp_f32_e32 v169, v169
	v_pk_mul_f32 v[162:163], v[160:161], v[162:163] op_sel_hi:[0,1]
	v_pk_mul_f32 v[164:165], v[160:161], v[164:165] op_sel_hi:[0,1]
	v_pk_mul_f32 v[166:167], v[160:161], v[166:167] op_sel_hi:[0,1]
	v_pk_mul_f32 v[168:169], v[160:161], v[168:169] op_sel_hi:[0,1]
; __device__ __forceinline__ unsigned cvt_pk_bf16(float lo, float hi) { unsigned r; asm volatile("v_cvt_pk_bf16_f32 %0, %1, %2" : "=v"(r) : "v"(lo), "v"(hi)); return r; }
;     __device__ __forceinline__ void operator()(Acc& acc, const Unit& u, int wr, int wc, int fr, int fq) const {
;     ...
;             for (int m = 0; m < 4; ++m) {
;                 const int row = row0 + ai * HALF + m * 16;
;                 const float r = rs[u.idx * BM + wr * 64 + fr + ai * HALF + m * 16];
;                 const float c1 = -r * 1.4426950408889634f, r2 = r * r;
;                 f32x4 o[2];
; #pragma unroll
;                 for (int n = 0; n < 2; ++n) {
;                     const f32x4 g = acc[ai][0][m][n], up = acc[ai][1][m][n];
;                     const f32x4 t = g * c1; f32x4 e;
; #pragma unroll
;                     for (int i = 0; i < 4; ++i) e[i] = __builtin_amdgcn_exp2f(t[i]);
;                     const f32x4 d = e + 1.0f; f32x4 q;
; #pragma unroll
;                     for (int i = 0; i < 4; ++i) q[i] = __builtin_amdgcn_rcpf(d[i]);
;                     o[n] = (g * up) * (q * r2);
;                 }
;                 u32x4 w; w.x = cvt_pk_bf16(o[0][0], o[0][1]); w.y = cvt_pk_bf16(o[0][2], o[0][3]); w.z = cvt_pk_bf16(o[1][0], o[1][1]); w.w = cvt_pk_bf16(o[1][2], o[1][3]);
;                 *(u32x4*)(O + (size_t)row * DFF + col0) = w;
	v_pk_mul_f32 v[88:89], v[88:89], v[162:163]
	v_pk_mul_f32 v[90:91], v[90:91], v[164:165]
	v_pk_mul_f32 v[80:81], v[80:81], v[166:167]
	v_pk_mul_f32 v[82:83], v[82:83], v[168:169]
	v_cvt_pk_bf16_f32 v170, v88, v89
	v_cvt_pk_bf16_f32 v171, v90, v91
	v_cvt_pk_bf16_f32 v172, v80, v81
	v_cvt_pk_bf16_f32 v173, v82, v83
	v_add_u32_e32 v174, 0x2c000, v155
	global_store_dwordx4 v174, v[170:173], s[64:65] sc1 nt
	v_mul_f32_e32 v158, 0xbfb8aa3b, v203
	v_mul_f32_e32 v160, v203, v203
	v_pk_mul_f32 v[162:163], v[76:77], v[158:159] op_sel_hi:[1,0]
	v_pk_mul_f32 v[164:165], v[78:79], v[158:159] op_sel_hi:[1,0]
	v_pk_mul_f32 v[166:167], v[68:69], v[158:159] op_sel_hi:[1,0]
	v_pk_mul_f32 v[168:169], v[70:71], v[158:159] op_sel_hi:[1,0]
	v_exp_f32_e32 v162, v162
	v_exp_f32_e32 v163, v163
	v_pk_mul_f32 v[72:73], v[76:77], v[72:73]
	v_exp_f32_e32 v164, v164
	v_exp_f32_e32 v165, v165
	v_pk_mul_f32 v[74:75], v[78:79], v[74:75]
	v_exp_f32_e32 v166, v166
	v_exp_f32_e32 v167, v167
	v_pk_mul_f32 v[64:65], v[68:69], v[64:65]
	v_exp_f32_e32 v168, v168
	v_exp_f32_e32 v169, v169
	v_pk_mul_f32 v[66:67], v[70:71], v[66:67]
	v_pk_add_f32 v[162:163], v[162:163], v[198:199] op_sel_hi:[1,0]
	v_pk_add_f32 v[164:165], v[164:165], v[198:199] op_sel_hi:[1,0]
	v_pk_add_f32 v[166:167], v[166:167], v[198:199] op_sel_hi:[1,0]
	v_pk_add_f32 v[168:169], v[168:169], v[198:199] op_sel_hi:[1,0]
	v_rcp_f32_e32 v162, v162
	v_rcp_f32_e32 v163, v163
	v_rcp_f32_e32 v164, v164
	v_rcp_f32_e32 v165, v165
	v_rcp_f32_e32 v166, v166
	v_rcp_f32_e32 v167, v167
	v_rcp_f32_e32 v168, v168
	v_rcp_f32_e32 v169, v169
	v_pk_mul_f32 v[162:163], v[160:161], v[162:163] op_sel_hi:[0,1]
	v_pk_mul_f32 v[164:165], v[160:161], v[164:165] op_sel_hi:[0,1]
	v_pk_mul_f32 v[166:167], v[160:161], v[166:167] op_sel_hi:[0,1]
	v_pk_mul_f32 v[168:169], v[160:161], v[168:169] op_sel_hi:[0,1]
	v_pk_mul_f32 v[72:73], v[72:73], v[162:163]
	v_pk_mul_f32 v[74:75], v[74:75], v[164:165]
	v_pk_mul_f32 v[64:65], v[64:65], v[166:167]
	v_pk_mul_f32 v[66:67], v[66:67], v[168:169]
	v_cvt_pk_bf16_f32 v176, v72, v73
	v_cvt_pk_bf16_f32 v177, v74, v75
	v_cvt_pk_bf16_f32 v178, v64, v65
	v_cvt_pk_bf16_f32 v179, v66, v67
	v_add_u32_e32 v175, 0x42000, v155
	global_store_dwordx4 v175, v[176:179], s[64:65] sc1 nt
	v_mul_f32_e32 v158, 0xbfb8aa3b, v204
	v_mul_f32_e32 v160, v204, v204
	v_pk_mul_f32 v[162:163], v[60:61], v[158:159] op_sel_hi:[1,0]
	v_pk_mul_f32 v[164:165], v[62:63], v[158:159] op_sel_hi:[1,0]
	v_pk_mul_f32 v[166:167], v[52:53], v[158:159] op_sel_hi:[1,0]
	v_pk_mul_f32 v[168:169], v[54:55], v[158:159] op_sel_hi:[1,0]
	v_exp_f32_e32 v162, v162
	v_exp_f32_e32 v163, v163
	v_pk_mul_f32 v[56:57], v[60:61], v[56:57]
	v_exp_f32_e32 v164, v164
	v_exp_f32_e32 v165, v165
	v_pk_mul_f32 v[58:59], v[62:63], v[58:59]
	v_exp_f32_e32 v166, v166
	v_exp_f32_e32 v167, v167
	v_pk_mul_f32 v[48:49], v[52:53], v[48:49]
	v_exp_f32_e32 v168, v168
	v_exp_f32_e32 v169, v169
	v_pk_mul_f32 v[50:51], v[54:55], v[50:51]
	v_pk_add_f32 v[162:163], v[162:163], v[198:199] op_sel_hi:[1,0]
	v_pk_add_f32 v[164:165], v[164:165], v[198:199] op_sel_hi:[1,0]
	v_pk_add_f32 v[166:167], v[166:167], v[198:199] op_sel_hi:[1,0]
	v_pk_add_f32 v[168:169], v[168:169], v[198:199] op_sel_hi:[1,0]
	v_rcp_f32_e32 v162, v162
	v_rcp_f32_e32 v163, v163
	v_rcp_f32_e32 v164, v164
	v_rcp_f32_e32 v165, v165
	v_rcp_f32_e32 v166, v166
	v_rcp_f32_e32 v167, v167
	v_rcp_f32_e32 v168, v168
	v_rcp_f32_e32 v169, v169
	v_pk_mul_f32 v[162:163], v[160:161], v[162:163] op_sel_hi:[0,1]
	v_pk_mul_f32 v[164:165], v[160:161], v[164:165] op_sel_hi:[0,1]
	v_pk_mul_f32 v[166:167], v[160:161], v[166:167] op_sel_hi:[0,1]
	v_pk_mul_f32 v[168:169], v[160:161], v[168:169] op_sel_hi:[0,1]
	v_pk_mul_f32 v[56:57], v[56:57], v[162:163]
	v_pk_mul_f32 v[58:59], v[58:59], v[164:165]
	v_pk_mul_f32 v[48:49], v[48:49], v[166:167]
	v_pk_mul_f32 v[50:51], v[50:51], v[168:169]
	v_cvt_pk_bf16_f32 v170, v56, v57
	v_cvt_pk_bf16_f32 v171, v58, v59
	v_cvt_pk_bf16_f32 v172, v48, v49
	v_cvt_pk_bf16_f32 v173, v50, v51
	v_add_u32_e32 v174, 0xb0000, v155
	global_store_dwordx4 v174, v[170:173], s[64:65] sc1 nt
	v_mul_f32_e32 v158, 0xbfb8aa3b, v205
	v_mul_f32_e32 v160, v205, v205
	v_pk_mul_f32 v[162:163], v[44:45], v[158:159] op_sel_hi:[1,0]
	v_pk_mul_f32 v[164:165], v[46:47], v[158:159] op_sel_hi:[1,0]
	v_pk_mul_f32 v[166:167], v[36:37], v[158:159] op_sel_hi:[1,0]
	v_pk_mul_f32 v[168:169], v[38:39], v[158:159] op_sel_hi:[1,0]
	v_exp_f32_e32 v162, v162
	v_exp_f32_e32 v163, v163
	v_pk_mul_f32 v[40:41], v[44:45], v[40:41]
	v_exp_f32_e32 v164, v164
	v_exp_f32_e32 v165, v165
	v_pk_mul_f32 v[42:43], v[46:47], v[42:43]
	v_exp_f32_e32 v166, v166
	v_exp_f32_e32 v167, v167
	v_pk_mul_f32 v[32:33], v[36:37], v[32:33]
	v_exp_f32_e32 v168, v168
	v_exp_f32_e32 v169, v169
	v_pk_mul_f32 v[34:35], v[38:39], v[34:35]
	v_pk_add_f32 v[162:163], v[162:163], v[198:199] op_sel_hi:[1,0]
; __device__ __forceinline__ unsigned cvt_pk_bf16(float lo, float hi) { unsigned r; asm volatile("v_cvt_pk_bf16_f32 %0, %1, %2" : "=v"(r) : "v"(lo), "v"(hi)); return r; }
; #define PG8_BAR __builtin_amdgcn_s_barrier()
;     __device__ __forceinline__ void operator()(Acc& acc, const Unit& u, int wr, int wc, int fr, int fq) const {
;     ...
;                     const f32x4 g = acc[ai][0][m][n], up = acc[ai][1][m][n];
;                     const f32x4 t = g * c1; f32x4 e;
; #pragma unroll
;                     for (int i = 0; i < 4; ++i) e[i] = __builtin_amdgcn_exp2f(t[i]);
;                     const f32x4 d = e + 1.0f; f32x4 q;
; #pragma unroll
;                     for (int i = 0; i < 4; ++i) q[i] = __builtin_amdgcn_rcpf(d[i]);
;                     o[n] = (g * up) * (q * r2);
;                 }
;                 u32x4 w; w.x = cvt_pk_bf16(o[0][0], o[0][1]); w.y = cvt_pk_bf16(o[0][2], o[0][3]); w.z = cvt_pk_bf16(o[1][0], o[1][1]); w.w = cvt_pk_bf16(o[1][2], o[1][3]);
;                 *(u32x4*)(O + (size_t)row * DFF + col0) = w;
; template <class Epi, class Sched, bool ALIGN_EPI>
; __device__ __forceinline__ void gemm_phase(LAS unsigned char* lds, const Gemm g, const Sched& S, const Epi& E) {
;     ...
;         if (!has_next) break;
; #pragma unroll
;         for (int a = 0; a < 2; ++a)
; #pragma unroll
;             for (int b = 0; b < 2; ++b)
; #pragma unroll
;                 for (int m = 0; m < 4; ++m)
; #pragma unroll
;                     for (int n = 0; n < 2; ++n) acc[a][b][m][n] = (f32x4){0.f, 0.f, 0.f, 0.f};
;         cur = nxt; cA = nA; cB = nB; ++ui;
;         if constexpr (ALIGN_EPI) { if (wr == 1) PG8_BAR; }
	v_pk_add_f32 v[164:165], v[164:165], v[198:199] op_sel_hi:[1,0]
	v_pk_add_f32 v[166:167], v[166:167], v[198:199] op_sel_hi:[1,0]
	v_pk_add_f32 v[168:169], v[168:169], v[198:199] op_sel_hi:[1,0]
	v_rcp_f32_e32 v162, v162
	v_rcp_f32_e32 v163, v163
	v_rcp_f32_e32 v164, v164
	v_rcp_f32_e32 v165, v165
	v_rcp_f32_e32 v166, v166
	v_rcp_f32_e32 v167, v167
	v_rcp_f32_e32 v168, v168
	v_rcp_f32_e32 v169, v169
	v_pk_mul_f32 v[162:163], v[160:161], v[162:163] op_sel_hi:[0,1]
	v_pk_mul_f32 v[164:165], v[160:161], v[164:165] op_sel_hi:[0,1]
	v_pk_mul_f32 v[166:167], v[160:161], v[166:167] op_sel_hi:[0,1]
	v_pk_mul_f32 v[168:169], v[160:161], v[168:169] op_sel_hi:[0,1]
	v_pk_mul_f32 v[40:41], v[40:41], v[162:163]
	v_pk_mul_f32 v[42:43], v[42:43], v[164:165]
	v_pk_mul_f32 v[32:33], v[32:33], v[166:167]
	v_pk_mul_f32 v[34:35], v[34:35], v[168:169]
	v_cvt_pk_bf16_f32 v176, v40, v41
	v_cvt_pk_bf16_f32 v177, v42, v43
	v_cvt_pk_bf16_f32 v178, v32, v33
	v_cvt_pk_bf16_f32 v179, v34, v35
	v_add_u32_e32 v175, 0xc6000, v155
	global_store_dwordx4 v175, v[176:179], s[64:65] sc1 nt
	v_mul_f32_e32 v158, 0xbfb8aa3b, v206
	v_mul_f32_e32 v160, v206, v206
	v_pk_mul_f32 v[162:163], v[28:29], v[158:159] op_sel_hi:[1,0]
	v_pk_mul_f32 v[164:165], v[30:31], v[158:159] op_sel_hi:[1,0]
	v_pk_mul_f32 v[166:167], v[20:21], v[158:159] op_sel_hi:[1,0]
	v_pk_mul_f32 v[168:169], v[22:23], v[158:159] op_sel_hi:[1,0]
	v_exp_f32_e32 v162, v162
	v_exp_f32_e32 v163, v163
	v_pk_mul_f32 v[24:25], v[28:29], v[24:25]
	v_exp_f32_e32 v164, v164
	v_exp_f32_e32 v165, v165
	v_pk_mul_f32 v[26:27], v[30:31], v[26:27]
	v_exp_f32_e32 v166, v166
	v_exp_f32_e32 v167, v167
	v_pk_mul_f32 v[16:17], v[20:21], v[16:17]
	v_exp_f32_e32 v168, v168
	v_exp_f32_e32 v169, v169
	v_pk_mul_f32 v[18:19], v[22:23], v[18:19]
	v_pk_add_f32 v[162:163], v[162:163], v[198:199] op_sel_hi:[1,0]
	v_pk_add_f32 v[164:165], v[164:165], v[198:199] op_sel_hi:[1,0]
	v_pk_add_f32 v[166:167], v[166:167], v[198:199] op_sel_hi:[1,0]
	v_pk_add_f32 v[168:169], v[168:169], v[198:199] op_sel_hi:[1,0]
	v_rcp_f32_e32 v162, v162
	v_rcp_f32_e32 v163, v163
	v_rcp_f32_e32 v164, v164
	v_rcp_f32_e32 v165, v165
	v_rcp_f32_e32 v166, v166
	v_rcp_f32_e32 v167, v167
	v_rcp_f32_e32 v168, v168
	v_rcp_f32_e32 v169, v169
	v_pk_mul_f32 v[162:163], v[160:161], v[162:163] op_sel_hi:[0,1]
	v_pk_mul_f32 v[164:165], v[160:161], v[164:165] op_sel_hi:[0,1]
	v_pk_mul_f32 v[166:167], v[160:161], v[166:167] op_sel_hi:[0,1]
	v_pk_mul_f32 v[168:169], v[160:161], v[168:169] op_sel_hi:[0,1]
	v_pk_mul_f32 v[24:25], v[24:25], v[162:163]
	v_pk_mul_f32 v[26:27], v[26:27], v[164:165]
	v_pk_mul_f32 v[16:17], v[16:17], v[166:167]
	v_pk_mul_f32 v[18:19], v[18:19], v[168:169]
	v_cvt_pk_bf16_f32 v170, v24, v25
	v_cvt_pk_bf16_f32 v171, v26, v27
	v_cvt_pk_bf16_f32 v172, v16, v17
	v_cvt_pk_bf16_f32 v173, v18, v19
	v_add_u32_e32 v174, 0xdc000, v155
	global_store_dwordx4 v174, v[170:173], s[64:65] sc1 nt
	v_mul_f32_e32 v158, 0xbfb8aa3b, v207
	v_mul_f32_e32 v160, v207, v207
	v_pk_mul_f32 v[162:163], v[12:13], v[158:159] op_sel_hi:[1,0]
	v_pk_mul_f32 v[164:165], v[14:15], v[158:159] op_sel_hi:[1,0]
	v_pk_mul_f32 v[166:167], v[4:5], v[158:159] op_sel_hi:[1,0]
	v_pk_mul_f32 v[168:169], v[6:7], v[158:159] op_sel_hi:[1,0]
	v_exp_f32_e32 v162, v162
	v_exp_f32_e32 v163, v163
	v_pk_mul_f32 v[8:9], v[12:13], v[8:9]
	v_exp_f32_e32 v164, v164
	v_exp_f32_e32 v165, v165
	v_pk_mul_f32 v[10:11], v[14:15], v[10:11]
	v_exp_f32_e32 v166, v166
	v_exp_f32_e32 v167, v167
	v_pk_mul_f32 v[0:1], v[4:5], v[0:1]
	v_exp_f32_e32 v168, v168
	v_exp_f32_e32 v169, v169
	v_pk_mul_f32 v[2:3], v[6:7], v[2:3]
	v_pk_add_f32 v[162:163], v[162:163], v[198:199] op_sel_hi:[1,0]
	v_pk_add_f32 v[164:165], v[164:165], v[198:199] op_sel_hi:[1,0]
	v_pk_add_f32 v[166:167], v[166:167], v[198:199] op_sel_hi:[1,0]
	v_pk_add_f32 v[168:169], v[168:169], v[198:199] op_sel_hi:[1,0]
	v_rcp_f32_e32 v162, v162
	v_rcp_f32_e32 v163, v163
	v_rcp_f32_e32 v164, v164
	v_rcp_f32_e32 v165, v165
	v_rcp_f32_e32 v166, v166
	v_rcp_f32_e32 v167, v167
	v_rcp_f32_e32 v168, v168
	v_rcp_f32_e32 v169, v169
	v_pk_mul_f32 v[162:163], v[160:161], v[162:163] op_sel_hi:[0,1]
	v_pk_mul_f32 v[164:165], v[160:161], v[164:165] op_sel_hi:[0,1]
	v_pk_mul_f32 v[166:167], v[160:161], v[166:167] op_sel_hi:[0,1]
	v_pk_mul_f32 v[168:169], v[160:161], v[168:169] op_sel_hi:[0,1]
	v_pk_mul_f32 v[8:9], v[8:9], v[162:163]
	v_pk_mul_f32 v[10:11], v[10:11], v[164:165]
	v_pk_mul_f32 v[0:1], v[0:1], v[166:167]
	v_pk_mul_f32 v[2:3], v[2:3], v[168:169]
	v_cvt_pk_bf16_f32 v176, v8, v9
	v_cvt_pk_bf16_f32 v177, v10, v11
	v_cvt_pk_bf16_f32 v178, v0, v1
	v_cvt_pk_bf16_f32 v179, v2, v3
	v_add_u32_e32 v175, 0xf2000, v155
	global_store_dwordx4 v175, v[176:179], s[64:65] sc1 nt
	s_andn2_b64 vcc, exec, s[2:3]
	s_mov_b64 s[2:3], -1
	s_mov_b32 s101, 1
	s_cbranch_vccnz .LBB0_1609
	s_andn2_b64 vcc, exec, s[4:5]
	s_cbranch_vccnz .LBB0_1608
	s_barrier
	s_branch .LBB0_1608
